# K-split GEMM phases (P4/P6/P9/P12): LDS-DMA prefetch of phases 3-4 issued with empty EXEC in the last K iteration of a workgroup's last unit (nothing consumes it)
# speedup vs baseline: 1.0057x; 1.0057x over previous
.LBB0_424:
	ds_read_b128 v[150:153], v163
	ds_read_b128 v[154:157], v163 offset:1024
	ds_read_b128 v[166:169], v163 offset:2048
	ds_read_b128 v[170:173], v163 offset:3072
	ds_read_b128 v[174:177], v164
	ds_read_b128 v[178:181], v164 offset:1024
	ds_read_b128 v[182:185], v164 offset:2048
	ds_read_b128 v[186:189], v164 offset:3072
	s_add_i32 s25, s24, 2
	s_add_u32 s48, s6, 0xffea0080
	s_addc_u32 s49, s7, -1
	s_cmp_eq_u32 s78, s24
	s_cselect_b32 s51, s74, s49
	s_cselect_b32 s50, s75, s48
	s_cselect_b32 s49, s76, s80
	s_cselect_b32 s48, s77, s79
	s_cselect_b64 s[100:101], s[42:43], -1
	v_lshl_add_u64 v[158:159], s[6:7], 0, v[142:143]
	s_add_i32 m0, s53, 0xc000
	ds_read_b128 v[190:193], v165
	ds_read_b128 v[194:197], v165 offset:1024
	ds_read_b128 v[198:201], v165 offset:2048
	ds_read_b128 v[202:205], v165 offset:3072
	ds_read_b128 v[206:209], v165 offset:4096
	ds_read_b128 v[210:213], v165 offset:5120
	ds_read_b128 v[214:217], v165 offset:6144
	ds_read_b128 v[218:221], v165 offset:7168
	global_load_lds_dwordx4 v[158:159], off
	v_lshl_add_u64 v[158:159], s[6:7], 0, v[144:145]
	s_add_i32 m0, s53, 0xe000
	s_nop 0
	global_load_lds_dwordx4 v[158:159], off
	s_waitcnt vmcnt(8)
	s_waitcnt lgkmcnt(0)
	s_barrier
	s_setprio 1
	s_waitcnt lgkmcnt(0)
	v_mfma_f32_16x16x32_bf16 v[86:89], v[150:153], v[190:193], v[86:89]
	v_mfma_f32_16x16x32_bf16 v[78:81], v[166:169], v[190:193], v[78:81]
	v_mfma_f32_16x16x32_bf16 v[66:69], v[150:153], v[198:201], v[66:69]
	v_mfma_f32_16x16x32_bf16 v[62:65], v[166:169], v[198:201], v[62:65]
	v_mfma_f32_16x16x32_bf16 v[54:57], v[150:153], v[206:209], v[54:57]
	v_mfma_f32_16x16x32_bf16 v[46:49], v[166:169], v[206:209], v[46:49]
	v_mfma_f32_16x16x32_bf16 v[38:41], v[150:153], v[214:217], v[38:41]
	v_mfma_f32_16x16x32_bf16 v[30:33], v[166:169], v[214:217], v[30:33]
	v_mfma_f32_16x16x32_bf16 v[86:89], v[154:157], v[194:197], v[86:89]
	v_mfma_f32_16x16x32_bf16 v[78:81], v[170:173], v[194:197], v[78:81]
	v_mfma_f32_16x16x32_bf16 v[66:69], v[154:157], v[202:205], v[66:69]
	v_mfma_f32_16x16x32_bf16 v[62:65], v[170:173], v[202:205], v[62:65]
	v_mfma_f32_16x16x32_bf16 v[54:57], v[154:157], v[210:213], v[54:57]
	v_mfma_f32_16x16x32_bf16 v[46:49], v[170:173], v[210:213], v[46:49]
	v_mfma_f32_16x16x32_bf16 v[38:41], v[154:157], v[218:221], v[38:41]
	v_mfma_f32_16x16x32_bf16 v[30:33], v[170:173], v[218:221], v[30:33]
	s_setprio 0
	s_setprio 1
	v_mfma_f32_16x16x32_bf16 v[50:53], v[174:177], v[190:193], v[50:53]
	v_mfma_f32_16x16x32_bf16 v[42:45], v[182:185], v[190:193], v[42:45]
	v_mfma_f32_16x16x32_bf16 v[34:37], v[174:177], v[198:201], v[34:37]
	v_mfma_f32_16x16x32_bf16 v[26:29], v[182:185], v[198:201], v[26:29]
	v_mfma_f32_16x16x32_bf16 v[22:25], v[174:177], v[206:209], v[22:25]
	v_mfma_f32_16x16x32_bf16 v[18:21], v[182:185], v[206:209], v[18:21]
	v_mfma_f32_16x16x32_bf16 v[10:13], v[174:177], v[214:217], v[10:13]
	v_mfma_f32_16x16x32_bf16 v[6:9], v[182:185], v[214:217], v[6:9]
	v_mfma_f32_16x16x32_bf16 v[50:53], v[178:181], v[194:197], v[50:53]
	v_mfma_f32_16x16x32_bf16 v[42:45], v[186:189], v[194:197], v[42:45]
	v_mfma_f32_16x16x32_bf16 v[34:37], v[178:181], v[202:205], v[34:37]
	v_mfma_f32_16x16x32_bf16 v[26:29], v[186:189], v[202:205], v[26:29]
	v_mfma_f32_16x16x32_bf16 v[22:25], v[178:181], v[210:213], v[22:25]
	v_mfma_f32_16x16x32_bf16 v[18:21], v[186:189], v[210:213], v[18:21]
	v_mfma_f32_16x16x32_bf16 v[10:13], v[178:181], v[218:221], v[10:13]
	v_mfma_f32_16x16x32_bf16 v[6:9], v[186:189], v[218:221], v[6:9]
	s_setprio 0
	s_barrier
	s_add_i32 s24, s66, s52
	v_lshl_add_u64 v[158:159], s[48:49], 0, v[132:133]
	s_mov_b32 m0, s24
	ds_read_b128 v[190:193], v165 offset:16384
	ds_read_b128 v[194:197], v165 offset:17408
	ds_read_b128 v[198:201], v165 offset:18432
	ds_read_b128 v[202:205], v165 offset:19456
	ds_read_b128 v[206:209], v165 offset:20480
	ds_read_b128 v[210:213], v165 offset:21504
	ds_read_b128 v[214:217], v165 offset:22528
	ds_read_b128 v[218:221], v165 offset:23552
	global_load_lds_dwordx4 v[158:159], off
	s_add_i32 m0, s24, 0x2000
	s_add_u32 s82, s48, 0x160000
	v_lshl_add_u64 v[222:223], s[48:49], 0, v[136:137]
	s_addc_u32 s83, s49, 0
	s_add_i32 s24, s67, s52
	global_load_lds_dwordx4 v[222:223], off
	v_lshl_add_u64 v[224:225], s[82:83], 0, v[132:133]
	s_mov_b32 m0, s24
	v_lshl_add_u64 v[226:227], s[50:51], 0, v[134:135]
	global_load_lds_dwordx4 v[224:225], off
	v_lshl_add_u64 v[224:225], s[82:83], 0, v[136:137]
	s_add_i32 m0, s24, 0x2000
	s_nop 0
	global_load_lds_dwordx4 v[224:225], off
	v_lshl_add_u64 v[224:225], s[50:51], 0, v[130:131]
	s_mov_b32 m0, s53
	s_nop 0
	global_load_lds_dwordx4 v[224:225], off
	s_mov_b32 m0, s54
	s_nop 0
	global_load_lds_dwordx4 v[226:227], off
	s_waitcnt vmcnt(8)
	s_waitcnt lgkmcnt(0)
	s_barrier
	s_setprio 1
	s_waitcnt lgkmcnt(0)
	v_mfma_f32_16x16x32_bf16 v[126:129], v[150:153], v[190:193], v[126:129]
	v_mfma_f32_16x16x32_bf16 v[122:125], v[166:169], v[190:193], v[122:125]
	v_mfma_f32_16x16x32_bf16 v[110:113], v[150:153], v[198:201], v[110:113]
	v_mfma_f32_16x16x32_bf16 v[106:109], v[166:169], v[198:201], v[106:109]
	v_mfma_f32_16x16x32_bf16 v[94:97], v[150:153], v[206:209], v[94:97]
	v_mfma_f32_16x16x32_bf16 v[90:93], v[166:169], v[206:209], v[90:93]
	v_mfma_f32_16x16x32_bf16 v[70:73], v[150:153], v[214:217], v[70:73]
	v_mfma_f32_16x16x32_bf16 v[58:61], v[166:169], v[214:217], v[58:61]
	v_mfma_f32_16x16x32_bf16 v[126:129], v[154:157], v[194:197], v[126:129]
	v_mfma_f32_16x16x32_bf16 v[122:125], v[170:173], v[194:197], v[122:125]
	v_mfma_f32_16x16x32_bf16 v[110:113], v[154:157], v[202:205], v[110:113]
	v_mfma_f32_16x16x32_bf16 v[106:109], v[170:173], v[202:205], v[106:109]
	v_mfma_f32_16x16x32_bf16 v[94:97], v[154:157], v[210:213], v[94:97]
	v_mfma_f32_16x16x32_bf16 v[90:93], v[170:173], v[210:213], v[90:93]
	v_mfma_f32_16x16x32_bf16 v[70:73], v[154:157], v[218:221], v[70:73]
	v_mfma_f32_16x16x32_bf16 v[58:61], v[170:173], v[218:221], v[58:61]
	s_setprio 0
	s_setprio 1
	v_mfma_f32_16x16x32_bf16 v[118:121], v[174:177], v[190:193], v[118:121]
	v_mfma_f32_16x16x32_bf16 v[114:117], v[182:185], v[190:193], v[114:117]
	v_mfma_f32_16x16x32_bf16 v[102:105], v[174:177], v[198:201], v[102:105]
	v_mfma_f32_16x16x32_bf16 v[98:101], v[182:185], v[198:201], v[98:101]
	v_mfma_f32_16x16x32_bf16 v[82:85], v[174:177], v[206:209], v[82:85]
	v_mfma_f32_16x16x32_bf16 v[74:77], v[182:185], v[206:209], v[74:77]
	v_mfma_f32_16x16x32_bf16 v[14:17], v[174:177], v[214:217], v[14:17]
	v_mfma_f32_16x16x32_bf16 v[2:5], v[182:185], v[214:217], v[2:5]
	v_mfma_f32_16x16x32_bf16 v[118:121], v[178:181], v[194:197], v[118:121]
	v_mfma_f32_16x16x32_bf16 v[114:117], v[186:189], v[194:197], v[114:117]
	v_mfma_f32_16x16x32_bf16 v[102:105], v[178:181], v[202:205], v[102:105]
	v_mfma_f32_16x16x32_bf16 v[98:101], v[186:189], v[202:205], v[98:101]
	v_mfma_f32_16x16x32_bf16 v[82:85], v[178:181], v[210:213], v[82:85]
	v_mfma_f32_16x16x32_bf16 v[74:77], v[186:189], v[210:213], v[74:77]
	v_mfma_f32_16x16x32_bf16 v[14:17], v[178:181], v[218:221], v[14:17]
	v_mfma_f32_16x16x32_bf16 v[2:5], v[186:189], v[218:221], v[2:5]
	s_setprio 0
	s_barrier
	s_add_i32 s24, 0, 0x18000
	v_add_u32_e32 v138, s24, v160
	s_add_i32 s81, 0, 0x1c000
	ds_read_b128 v[150:153], v138
	ds_read_b128 v[154:157], v138 offset:1024
	ds_read_b128 v[166:169], v138 offset:2048
	ds_read_b128 v[170:173], v138 offset:3072
	v_add_u32_e32 v138, s81, v160
	ds_read_b128 v[174:177], v138
	ds_read_b128 v[178:181], v138 offset:1024
	ds_read_b128 v[182:185], v138 offset:2048
	ds_read_b128 v[186:189], v138 offset:3072
	s_add_u32 s50, s50, 0x160000
	s_addc_u32 s51, s51, 0
	s_mov_b32 m0, s55
	v_lshl_add_u64 v[228:229], s[50:51], 0, v[130:131]
	ds_read_b128 v[190:193], v165 offset:32768
	ds_read_b128 v[194:197], v165 offset:33792
	ds_read_b128 v[198:201], v165 offset:34816
	ds_read_b128 v[202:205], v165 offset:35840
	ds_read_b128 v[206:209], v165 offset:36864
	ds_read_b128 v[210:213], v165 offset:37888
	ds_read_b128 v[214:217], v165 offset:38912
	ds_read_b128 v[218:221], v165 offset:39936
	s_mov_b64 exec, s[100:101]
	global_load_lds_dwordx4 v[228:229], off
	s_mov_b64 exec, -1
	v_lshl_add_u64 v[228:229], s[50:51], 0, v[134:135]
	s_mov_b32 m0, s56
	s_nop 0
	s_mov_b64 exec, s[100:101]
	global_load_lds_dwordx4 v[228:229], off
	s_mov_b64 exec, -1
	s_waitcnt vmcnt(8)
	s_waitcnt lgkmcnt(0)
	s_barrier
	s_setprio 1
	s_waitcnt lgkmcnt(0)
	v_mfma_f32_16x16x32_bf16 v[86:89], v[150:153], v[190:193], v[86:89]
	v_mfma_f32_16x16x32_bf16 v[78:81], v[166:169], v[190:193], v[78:81]
	v_mfma_f32_16x16x32_bf16 v[66:69], v[150:153], v[198:201], v[66:69]
	v_mfma_f32_16x16x32_bf16 v[62:65], v[166:169], v[198:201], v[62:65]
	v_mfma_f32_16x16x32_bf16 v[54:57], v[150:153], v[206:209], v[54:57]
	v_mfma_f32_16x16x32_bf16 v[46:49], v[166:169], v[206:209], v[46:49]
	v_mfma_f32_16x16x32_bf16 v[38:41], v[150:153], v[214:217], v[38:41]
	v_mfma_f32_16x16x32_bf16 v[30:33], v[166:169], v[214:217], v[30:33]
	v_mfma_f32_16x16x32_bf16 v[86:89], v[154:157], v[194:197], v[86:89]
	v_mfma_f32_16x16x32_bf16 v[78:81], v[170:173], v[194:197], v[78:81]
	v_mfma_f32_16x16x32_bf16 v[66:69], v[154:157], v[202:205], v[66:69]
	v_mfma_f32_16x16x32_bf16 v[62:65], v[170:173], v[202:205], v[62:65]
	v_mfma_f32_16x16x32_bf16 v[54:57], v[154:157], v[210:213], v[54:57]
	v_mfma_f32_16x16x32_bf16 v[46:49], v[170:173], v[210:213], v[46:49]
	v_mfma_f32_16x16x32_bf16 v[38:41], v[154:157], v[218:221], v[38:41]
	v_mfma_f32_16x16x32_bf16 v[30:33], v[170:173], v[218:221], v[30:33]
	s_setprio 0
	s_setprio 1
	v_mfma_f32_16x16x32_bf16 v[50:53], v[174:177], v[190:193], v[50:53]
	v_mfma_f32_16x16x32_bf16 v[42:45], v[182:185], v[190:193], v[42:45]
	v_mfma_f32_16x16x32_bf16 v[34:37], v[174:177], v[198:201], v[34:37]
	v_mfma_f32_16x16x32_bf16 v[26:29], v[182:185], v[198:201], v[26:29]
	v_mfma_f32_16x16x32_bf16 v[22:25], v[174:177], v[206:209], v[22:25]
	v_mfma_f32_16x16x32_bf16 v[18:21], v[182:185], v[206:209], v[18:21]
	v_mfma_f32_16x16x32_bf16 v[10:13], v[174:177], v[214:217], v[10:13]
	v_mfma_f32_16x16x32_bf16 v[6:9], v[182:185], v[214:217], v[6:9]
	v_mfma_f32_16x16x32_bf16 v[50:53], v[178:181], v[194:197], v[50:53]
	v_mfma_f32_16x16x32_bf16 v[42:45], v[186:189], v[194:197], v[42:45]
	v_mfma_f32_16x16x32_bf16 v[34:37], v[178:181], v[202:205], v[34:37]
	v_mfma_f32_16x16x32_bf16 v[26:29], v[186:189], v[202:205], v[26:29]
	v_mfma_f32_16x16x32_bf16 v[22:25], v[178:181], v[210:213], v[22:25]
	v_mfma_f32_16x16x32_bf16 v[18:21], v[186:189], v[210:213], v[18:21]
	v_mfma_f32_16x16x32_bf16 v[10:13], v[178:181], v[218:221], v[10:13]
	v_mfma_f32_16x16x32_bf16 v[6:9], v[186:189], v[218:221], v[6:9]
	s_setprio 0
	s_barrier
	s_add_i32 s24, s24, s52
	v_lshl_add_u64 v[158:159], v[158:159], 0, s[14:15]
	s_mov_b32 m0, s24
	ds_read_b128 v[190:193], v165 offset:49152
	ds_read_b128 v[194:197], v165 offset:50176
	ds_read_b128 v[198:201], v165 offset:51200
	ds_read_b128 v[202:205], v165 offset:52224
	ds_read_b128 v[206:209], v165 offset:53248
	ds_read_b128 v[210:213], v165 offset:54272
	ds_read_b128 v[214:217], v165 offset:55296
	ds_read_b128 v[218:221], v165 offset:56320
	s_mov_b64 exec, s[100:101]
	global_load_lds_dwordx4 v[158:159], off
	s_mov_b64 exec, -1
	s_add_i32 m0, s24, 0x2000
	s_add_u32 s48, s48, 0x160080
	v_lshl_add_u64 v[158:159], v[222:223], 0, s[14:15]
	s_addc_u32 s49, s49, 0
	s_add_i32 s24, s81, s52
	s_mov_b64 exec, s[100:101]
	global_load_lds_dwordx4 v[158:159], off
	s_mov_b64 exec, -1
	v_lshl_add_u64 v[158:159], s[48:49], 0, v[132:133]
	s_mov_b32 m0, s24
	s_nop 0
	s_mov_b64 exec, s[100:101]
	global_load_lds_dwordx4 v[158:159], off
	s_mov_b64 exec, -1
	v_lshl_add_u64 v[158:159], s[48:49], 0, v[136:137]
	s_add_i32 m0, s24, 0x2000
	s_nop 0
	s_mov_b64 exec, s[100:101]
	global_load_lds_dwordx4 v[158:159], off
	s_mov_b64 exec, -1
	v_lshl_add_u64 v[158:159], v[224:225], 0, s[14:15]
	s_mov_b32 m0, s62
	s_nop 0
	s_mov_b64 exec, s[100:101]
	global_load_lds_dwordx4 v[158:159], off
	s_mov_b64 exec, -1
	v_lshl_add_u64 v[158:159], v[226:227], 0, s[14:15]
	s_mov_b32 m0, s63
	s_nop 0
	s_mov_b64 exec, s[100:101]
	global_load_lds_dwordx4 v[158:159], off
	s_mov_b64 exec, -1
	s_waitcnt vmcnt(8)
	s_waitcnt lgkmcnt(0)
	s_barrier
	s_setprio 1
	s_waitcnt lgkmcnt(0)
	v_mfma_f32_16x16x32_bf16 v[126:129], v[150:153], v[190:193], v[126:129]
	v_mfma_f32_16x16x32_bf16 v[122:125], v[166:169], v[190:193], v[122:125]
	v_mfma_f32_16x16x32_bf16 v[110:113], v[150:153], v[198:201], v[110:113]
	v_mfma_f32_16x16x32_bf16 v[106:109], v[166:169], v[198:201], v[106:109]
	v_mfma_f32_16x16x32_bf16 v[94:97], v[150:153], v[206:209], v[94:97]
	v_mfma_f32_16x16x32_bf16 v[90:93], v[166:169], v[206:209], v[90:93]
	v_mfma_f32_16x16x32_bf16 v[70:73], v[150:153], v[214:217], v[70:73]
	v_mfma_f32_16x16x32_bf16 v[58:61], v[166:169], v[214:217], v[58:61]
	v_mfma_f32_16x16x32_bf16 v[126:129], v[154:157], v[194:197], v[126:129]
	v_mfma_f32_16x16x32_bf16 v[122:125], v[170:173], v[194:197], v[122:125]
	v_mfma_f32_16x16x32_bf16 v[110:113], v[154:157], v[202:205], v[110:113]
	v_mfma_f32_16x16x32_bf16 v[106:109], v[170:173], v[202:205], v[106:109]
	v_mfma_f32_16x16x32_bf16 v[94:97], v[154:157], v[210:213], v[94:97]
	v_mfma_f32_16x16x32_bf16 v[90:93], v[170:173], v[210:213], v[90:93]
	v_mfma_f32_16x16x32_bf16 v[70:73], v[154:157], v[218:221], v[70:73]
	v_mfma_f32_16x16x32_bf16 v[58:61], v[170:173], v[218:221], v[58:61]
	s_setprio 0
	s_setprio 1
	v_mfma_f32_16x16x32_bf16 v[118:121], v[174:177], v[190:193], v[118:121]
	v_mfma_f32_16x16x32_bf16 v[114:117], v[182:185], v[190:193], v[114:117]
	v_mfma_f32_16x16x32_bf16 v[102:105], v[174:177], v[198:201], v[102:105]
	v_mfma_f32_16x16x32_bf16 v[98:101], v[182:185], v[198:201], v[98:101]
	v_mfma_f32_16x16x32_bf16 v[82:85], v[174:177], v[206:209], v[82:85]
	v_mfma_f32_16x16x32_bf16 v[74:77], v[182:185], v[206:209], v[74:77]
	v_mfma_f32_16x16x32_bf16 v[14:17], v[174:177], v[214:217], v[14:17]
	v_mfma_f32_16x16x32_bf16 v[2:5], v[182:185], v[214:217], v[2:5]
	v_mfma_f32_16x16x32_bf16 v[118:121], v[178:181], v[194:197], v[118:121]
	v_mfma_f32_16x16x32_bf16 v[114:117], v[186:189], v[194:197], v[114:117]
	v_mfma_f32_16x16x32_bf16 v[102:105], v[178:181], v[202:205], v[102:105]
	v_mfma_f32_16x16x32_bf16 v[98:101], v[186:189], v[202:205], v[98:101]
	v_mfma_f32_16x16x32_bf16 v[82:85], v[178:181], v[210:213], v[82:85]
	v_mfma_f32_16x16x32_bf16 v[74:77], v[186:189], v[210:213], v[74:77]
	v_mfma_f32_16x16x32_bf16 v[14:17], v[178:181], v[218:221], v[14:17]
	v_mfma_f32_16x16x32_bf16 v[2:5], v[186:189], v[218:221], v[2:5]
	s_setprio 0
	s_barrier
	s_add_u32 s6, s6, 0x100
	s_addc_u32 s7, s7, 0
	s_add_u32 s79, s79, 0x100
	s_addc_u32 s80, s80, 0
	s_cmp_ge_i32 s25, s73
	s_mov_b32 s24, s25
	s_cbranch_scc0 .LBB0_424
	s_and_b64 vcc, exec, s[16:17]
	s_cbranch_vccz .LBB0_427
	s_barrier

.LBB0_587:
	ds_read_b128 v[156:159], v152
	ds_read_b128 v[164:167], v152 offset:1024
	ds_read_b128 v[168:171], v152 offset:2048
	ds_read_b128 v[172:175], v152 offset:3072
	ds_read_b128 v[176:179], v153
	ds_read_b128 v[180:183], v153 offset:1024
	ds_read_b128 v[184:187], v153 offset:2048
	ds_read_b128 v[188:191], v153 offset:3072
	s_add_i32 s25, s24, 2
	s_add_u32 s58, s56, 0xfff80080
	s_addc_u32 s59, s57, -1
	s_cmp_eq_u32 s82, s24
	s_cselect_b32 s61, s39, s59
	s_cselect_b32 s60, s49, s58
	s_cselect_b32 s59, s80, s84
	s_cselect_b32 s58, s81, s83
	s_cselect_b64 s[100:101], s[50:51], -1
	v_lshl_add_u64 v[150:151], s[56:57], 0, v[142:143]
	s_add_i32 m0, s62, 0xc000
	ds_read_b128 v[192:195], v154
	ds_read_b128 v[196:199], v154 offset:1024
	ds_read_b128 v[200:203], v154 offset:2048
	ds_read_b128 v[204:207], v154 offset:3072
	ds_read_b128 v[208:211], v154 offset:4096
	ds_read_b128 v[212:215], v154 offset:5120
	ds_read_b128 v[216:219], v154 offset:6144
	ds_read_b128 v[220:223], v154 offset:7168
	global_load_lds_dwordx4 v[150:151], off
	v_lshl_add_u64 v[150:151], s[56:57], 0, v[144:145]
	s_add_i32 m0, s62, 0xe000
	s_nop 0
	global_load_lds_dwordx4 v[150:151], off
	s_waitcnt vmcnt(8)
	s_waitcnt lgkmcnt(0)
	s_barrier
	s_setprio 1
	s_waitcnt lgkmcnt(0)
	v_mfma_f32_16x16x32_bf16 v[106:109], v[156:159], v[192:195], v[106:109]
	v_mfma_f32_16x16x32_bf16 v[98:101], v[168:171], v[192:195], v[98:101]
	v_mfma_f32_16x16x32_bf16 v[90:93], v[156:159], v[200:203], v[90:93]
	v_mfma_f32_16x16x32_bf16 v[82:85], v[168:171], v[200:203], v[82:85]
	v_mfma_f32_16x16x32_bf16 v[70:73], v[156:159], v[208:211], v[70:73]
	v_mfma_f32_16x16x32_bf16 v[62:65], v[168:171], v[208:211], v[62:65]
	v_mfma_f32_16x16x32_bf16 v[46:49], v[156:159], v[216:219], v[46:49]
	v_mfma_f32_16x16x32_bf16 v[38:41], v[168:171], v[216:219], v[38:41]
	v_mfma_f32_16x16x32_bf16 v[106:109], v[164:167], v[196:199], v[106:109]
	v_mfma_f32_16x16x32_bf16 v[98:101], v[172:175], v[196:199], v[98:101]
	v_mfma_f32_16x16x32_bf16 v[90:93], v[164:167], v[204:207], v[90:93]
	v_mfma_f32_16x16x32_bf16 v[82:85], v[172:175], v[204:207], v[82:85]
	v_mfma_f32_16x16x32_bf16 v[70:73], v[164:167], v[212:215], v[70:73]
	v_mfma_f32_16x16x32_bf16 v[62:65], v[172:175], v[212:215], v[62:65]
	v_mfma_f32_16x16x32_bf16 v[46:49], v[164:167], v[220:223], v[46:49]
	v_mfma_f32_16x16x32_bf16 v[38:41], v[172:175], v[220:223], v[38:41]
	s_setprio 0
	s_setprio 1
	v_mfma_f32_16x16x32_bf16 v[66:69], v[176:179], v[192:195], v[66:69]
	v_mfma_f32_16x16x32_bf16 v[58:61], v[184:187], v[192:195], v[58:61]
	v_mfma_f32_16x16x32_bf16 v[42:45], v[176:179], v[200:203], v[42:45]
	v_mfma_f32_16x16x32_bf16 v[34:37], v[184:187], v[200:203], v[34:37]
	v_mfma_f32_16x16x32_bf16 v[22:25], v[176:179], v[208:211], v[22:25]
	v_mfma_f32_16x16x32_bf16 v[18:21], v[184:187], v[208:211], v[18:21]
	v_mfma_f32_16x16x32_bf16 v[14:17], v[176:179], v[216:219], v[14:17]
	v_mfma_f32_16x16x32_bf16 v[6:9], v[184:187], v[216:219], v[6:9]
	v_mfma_f32_16x16x32_bf16 v[66:69], v[180:183], v[196:199], v[66:69]
	v_mfma_f32_16x16x32_bf16 v[58:61], v[188:191], v[196:199], v[58:61]
	v_mfma_f32_16x16x32_bf16 v[42:45], v[180:183], v[204:207], v[42:45]
	v_mfma_f32_16x16x32_bf16 v[34:37], v[188:191], v[204:207], v[34:37]
	v_mfma_f32_16x16x32_bf16 v[22:25], v[180:183], v[212:215], v[22:25]
	v_mfma_f32_16x16x32_bf16 v[18:21], v[188:191], v[212:215], v[18:21]
	v_mfma_f32_16x16x32_bf16 v[14:17], v[180:183], v[220:223], v[14:17]
	v_mfma_f32_16x16x32_bf16 v[6:9], v[188:191], v[220:223], v[6:9]
	s_setprio 0
	s_barrier
	s_add_i32 s24, s72, s31
	v_lshl_add_u64 v[150:151], s[58:59], 0, v[132:133]
	s_mov_b32 m0, s24
	ds_read_b128 v[192:195], v154 offset:16384
	ds_read_b128 v[196:199], v154 offset:17408
	ds_read_b128 v[200:203], v154 offset:18432
	ds_read_b128 v[204:207], v154 offset:19456
	ds_read_b128 v[208:211], v154 offset:20480
	ds_read_b128 v[212:215], v154 offset:21504
	ds_read_b128 v[216:219], v154 offset:22528
	ds_read_b128 v[220:223], v154 offset:23552
	global_load_lds_dwordx4 v[150:151], off
	s_add_i32 m0, s24, 0x2000
	s_add_u32 s86, s58, 0x80000
	v_lshl_add_u64 v[160:161], s[58:59], 0, v[136:137]
	s_addc_u32 s87, s59, 0
	s_add_i32 s24, s73, s31
	global_load_lds_dwordx4 v[160:161], off
	v_lshl_add_u64 v[224:225], s[86:87], 0, v[132:133]
	s_mov_b32 m0, s24
	v_lshl_add_u64 v[226:227], s[60:61], 0, v[134:135]
	global_load_lds_dwordx4 v[224:225], off
	v_lshl_add_u64 v[224:225], s[86:87], 0, v[136:137]
	s_add_i32 m0, s24, 0x2000
	s_nop 0
	global_load_lds_dwordx4 v[224:225], off
	v_lshl_add_u64 v[224:225], s[60:61], 0, v[130:131]
	s_mov_b32 m0, s62
	s_nop 0
	global_load_lds_dwordx4 v[224:225], off
	s_mov_b32 m0, s63
	s_nop 0
	global_load_lds_dwordx4 v[226:227], off
	s_waitcnt vmcnt(8)
	s_waitcnt lgkmcnt(0)
	s_barrier
	s_setprio 1
	s_waitcnt lgkmcnt(0)
	v_mfma_f32_16x16x32_bf16 v[126:129], v[156:159], v[192:195], v[126:129]
	v_mfma_f32_16x16x32_bf16 v[122:125], v[168:171], v[192:195], v[122:125]
	v_mfma_f32_16x16x32_bf16 v[118:121], v[156:159], v[200:203], v[118:121]
	v_mfma_f32_16x16x32_bf16 v[114:117], v[168:171], v[200:203], v[114:117]
	v_mfma_f32_16x16x32_bf16 v[94:97], v[156:159], v[208:211], v[94:97]
	v_mfma_f32_16x16x32_bf16 v[86:89], v[168:171], v[208:211], v[86:89]
	v_mfma_f32_16x16x32_bf16 v[54:57], v[156:159], v[216:219], v[54:57]
	v_mfma_f32_16x16x32_bf16 v[50:53], v[168:171], v[216:219], v[50:53]
	v_mfma_f32_16x16x32_bf16 v[126:129], v[164:167], v[196:199], v[126:129]
	v_mfma_f32_16x16x32_bf16 v[122:125], v[172:175], v[196:199], v[122:125]
	v_mfma_f32_16x16x32_bf16 v[118:121], v[164:167], v[204:207], v[118:121]
	v_mfma_f32_16x16x32_bf16 v[114:117], v[172:175], v[204:207], v[114:117]
	v_mfma_f32_16x16x32_bf16 v[94:97], v[164:167], v[212:215], v[94:97]
	v_mfma_f32_16x16x32_bf16 v[86:89], v[172:175], v[212:215], v[86:89]
	v_mfma_f32_16x16x32_bf16 v[54:57], v[164:167], v[220:223], v[54:57]
	v_mfma_f32_16x16x32_bf16 v[50:53], v[172:175], v[220:223], v[50:53]
	s_setprio 0
	s_setprio 1
	v_mfma_f32_16x16x32_bf16 v[110:113], v[176:179], v[192:195], v[110:113]
	v_mfma_f32_16x16x32_bf16 v[102:105], v[184:187], v[192:195], v[102:105]
	v_mfma_f32_16x16x32_bf16 v[78:81], v[176:179], v[200:203], v[78:81]
	v_mfma_f32_16x16x32_bf16 v[74:77], v[184:187], v[200:203], v[74:77]
	v_mfma_f32_16x16x32_bf16 v[30:33], v[176:179], v[208:211], v[30:33]
	v_mfma_f32_16x16x32_bf16 v[26:29], v[184:187], v[208:211], v[26:29]
	v_mfma_f32_16x16x32_bf16 v[10:13], v[176:179], v[216:219], v[10:13]
	v_mfma_f32_16x16x32_bf16 v[2:5], v[184:187], v[216:219], v[2:5]
	v_mfma_f32_16x16x32_bf16 v[110:113], v[180:183], v[196:199], v[110:113]
	v_mfma_f32_16x16x32_bf16 v[102:105], v[188:191], v[196:199], v[102:105]
	v_mfma_f32_16x16x32_bf16 v[78:81], v[180:183], v[204:207], v[78:81]
	v_mfma_f32_16x16x32_bf16 v[74:77], v[188:191], v[204:207], v[74:77]
	v_mfma_f32_16x16x32_bf16 v[30:33], v[180:183], v[212:215], v[30:33]
	v_mfma_f32_16x16x32_bf16 v[26:29], v[188:191], v[212:215], v[26:29]
	v_mfma_f32_16x16x32_bf16 v[10:13], v[180:183], v[220:223], v[10:13]
	v_mfma_f32_16x16x32_bf16 v[2:5], v[188:191], v[220:223], v[2:5]
	s_setprio 0
	s_barrier
	s_add_i32 s24, 0, 0x18000
	v_add_u32_e32 v155, s24, v1
	s_add_i32 s85, 0, 0x1c000
	ds_read_b128 v[156:159], v155
	ds_read_b128 v[164:167], v155 offset:1024
	ds_read_b128 v[168:171], v155 offset:2048
	ds_read_b128 v[172:175], v155 offset:3072
	v_add_u32_e32 v155, s85, v1
	ds_read_b128 v[176:179], v155
	ds_read_b128 v[180:183], v155 offset:1024
	ds_read_b128 v[184:187], v155 offset:2048
	ds_read_b128 v[188:191], v155 offset:3072
	s_add_u32 s60, s60, 0x80000
	s_addc_u32 s61, s61, 0
	s_mov_b32 m0, s64
	v_lshl_add_u64 v[228:229], s[60:61], 0, v[130:131]
	ds_read_b128 v[192:195], v154 offset:32768
	ds_read_b128 v[196:199], v154 offset:33792
	ds_read_b128 v[200:203], v154 offset:34816
	ds_read_b128 v[204:207], v154 offset:35840
	ds_read_b128 v[208:211], v154 offset:36864
	ds_read_b128 v[212:215], v154 offset:37888
	ds_read_b128 v[216:219], v154 offset:38912
	ds_read_b128 v[220:223], v154 offset:39936
	s_mov_b64 exec, s[100:101]
	global_load_lds_dwordx4 v[228:229], off
	s_mov_b64 exec, -1
	v_lshl_add_u64 v[228:229], s[60:61], 0, v[134:135]
	s_mov_b32 m0, s65
	s_nop 0
	s_mov_b64 exec, s[100:101]
	global_load_lds_dwordx4 v[228:229], off
	s_mov_b64 exec, -1
	s_waitcnt vmcnt(8)
	s_waitcnt lgkmcnt(0)
	s_barrier
	s_setprio 1
	s_waitcnt lgkmcnt(0)
	v_mfma_f32_16x16x32_bf16 v[106:109], v[156:159], v[192:195], v[106:109]
	v_mfma_f32_16x16x32_bf16 v[98:101], v[168:171], v[192:195], v[98:101]
	v_mfma_f32_16x16x32_bf16 v[90:93], v[156:159], v[200:203], v[90:93]
	v_mfma_f32_16x16x32_bf16 v[82:85], v[168:171], v[200:203], v[82:85]
	v_mfma_f32_16x16x32_bf16 v[70:73], v[156:159], v[208:211], v[70:73]
	v_mfma_f32_16x16x32_bf16 v[62:65], v[168:171], v[208:211], v[62:65]
	v_mfma_f32_16x16x32_bf16 v[46:49], v[156:159], v[216:219], v[46:49]
	v_mfma_f32_16x16x32_bf16 v[38:41], v[168:171], v[216:219], v[38:41]
	v_mfma_f32_16x16x32_bf16 v[106:109], v[164:167], v[196:199], v[106:109]
	v_mfma_f32_16x16x32_bf16 v[98:101], v[172:175], v[196:199], v[98:101]
	v_mfma_f32_16x16x32_bf16 v[90:93], v[164:167], v[204:207], v[90:93]
	v_mfma_f32_16x16x32_bf16 v[82:85], v[172:175], v[204:207], v[82:85]
	v_mfma_f32_16x16x32_bf16 v[70:73], v[164:167], v[212:215], v[70:73]
	v_mfma_f32_16x16x32_bf16 v[62:65], v[172:175], v[212:215], v[62:65]
	v_mfma_f32_16x16x32_bf16 v[46:49], v[164:167], v[220:223], v[46:49]
	v_mfma_f32_16x16x32_bf16 v[38:41], v[172:175], v[220:223], v[38:41]
	s_setprio 0
	s_setprio 1
	v_mfma_f32_16x16x32_bf16 v[66:69], v[176:179], v[192:195], v[66:69]
	v_mfma_f32_16x16x32_bf16 v[58:61], v[184:187], v[192:195], v[58:61]
	v_mfma_f32_16x16x32_bf16 v[42:45], v[176:179], v[200:203], v[42:45]
	v_mfma_f32_16x16x32_bf16 v[34:37], v[184:187], v[200:203], v[34:37]
	v_mfma_f32_16x16x32_bf16 v[22:25], v[176:179], v[208:211], v[22:25]
	v_mfma_f32_16x16x32_bf16 v[18:21], v[184:187], v[208:211], v[18:21]
	v_mfma_f32_16x16x32_bf16 v[14:17], v[176:179], v[216:219], v[14:17]
	v_mfma_f32_16x16x32_bf16 v[6:9], v[184:187], v[216:219], v[6:9]
	v_mfma_f32_16x16x32_bf16 v[66:69], v[180:183], v[196:199], v[66:69]
	v_mfma_f32_16x16x32_bf16 v[58:61], v[188:191], v[196:199], v[58:61]
	v_mfma_f32_16x16x32_bf16 v[42:45], v[180:183], v[204:207], v[42:45]
	v_mfma_f32_16x16x32_bf16 v[34:37], v[188:191], v[204:207], v[34:37]
	v_mfma_f32_16x16x32_bf16 v[22:25], v[180:183], v[212:215], v[22:25]
	v_mfma_f32_16x16x32_bf16 v[18:21], v[188:191], v[212:215], v[18:21]
	v_mfma_f32_16x16x32_bf16 v[14:17], v[180:183], v[220:223], v[14:17]
	v_mfma_f32_16x16x32_bf16 v[6:9], v[188:191], v[220:223], v[6:9]
	s_setprio 0
	s_barrier
	s_add_i32 s24, s24, s31
	v_lshl_add_u64 v[150:151], v[150:151], 0, s[12:13]
	s_mov_b32 m0, s24
	ds_read_b128 v[192:195], v154 offset:49152
	ds_read_b128 v[196:199], v154 offset:50176
	ds_read_b128 v[200:203], v154 offset:51200
	ds_read_b128 v[204:207], v154 offset:52224
	ds_read_b128 v[208:211], v154 offset:53248
	ds_read_b128 v[212:215], v154 offset:54272
	ds_read_b128 v[216:219], v154 offset:55296
	ds_read_b128 v[220:223], v154 offset:56320
	s_mov_b64 exec, s[100:101]
	global_load_lds_dwordx4 v[150:151], off
	s_mov_b64 exec, -1
	s_add_i32 m0, s24, 0x2000
	s_add_u32 s58, s58, 0x80080
	v_lshl_add_u64 v[150:151], v[160:161], 0, s[12:13]
	s_addc_u32 s59, s59, 0
	s_add_i32 s24, s85, s31
	s_mov_b64 exec, s[100:101]
	global_load_lds_dwordx4 v[150:151], off
	s_mov_b64 exec, -1
	v_lshl_add_u64 v[150:151], s[58:59], 0, v[132:133]
	s_mov_b32 m0, s24
	s_nop 0
	s_mov_b64 exec, s[100:101]
	global_load_lds_dwordx4 v[150:151], off
	s_mov_b64 exec, -1
	v_lshl_add_u64 v[150:151], s[58:59], 0, v[136:137]
	s_add_i32 m0, s24, 0x2000
	s_nop 0
	s_mov_b64 exec, s[100:101]
	global_load_lds_dwordx4 v[150:151], off
	s_mov_b64 exec, -1
	v_lshl_add_u64 v[150:151], v[224:225], 0, s[12:13]
	s_mov_b32 m0, s67
	s_nop 0
	s_mov_b64 exec, s[100:101]
	global_load_lds_dwordx4 v[150:151], off
	s_mov_b64 exec, -1
	v_lshl_add_u64 v[150:151], v[226:227], 0, s[12:13]
	s_mov_b32 m0, s68
	s_nop 0
	s_mov_b64 exec, s[100:101]
	global_load_lds_dwordx4 v[150:151], off
	s_mov_b64 exec, -1
	s_waitcnt vmcnt(8)
	s_waitcnt lgkmcnt(0)
	s_barrier
	s_setprio 1
	s_waitcnt lgkmcnt(0)
	v_mfma_f32_16x16x32_bf16 v[126:129], v[156:159], v[192:195], v[126:129]
	v_mfma_f32_16x16x32_bf16 v[122:125], v[168:171], v[192:195], v[122:125]
	v_mfma_f32_16x16x32_bf16 v[118:121], v[156:159], v[200:203], v[118:121]
	v_mfma_f32_16x16x32_bf16 v[114:117], v[168:171], v[200:203], v[114:117]
	v_mfma_f32_16x16x32_bf16 v[94:97], v[156:159], v[208:211], v[94:97]
	v_mfma_f32_16x16x32_bf16 v[86:89], v[168:171], v[208:211], v[86:89]
	v_mfma_f32_16x16x32_bf16 v[54:57], v[156:159], v[216:219], v[54:57]
	v_mfma_f32_16x16x32_bf16 v[50:53], v[168:171], v[216:219], v[50:53]
	v_mfma_f32_16x16x32_bf16 v[126:129], v[164:167], v[196:199], v[126:129]
	v_mfma_f32_16x16x32_bf16 v[122:125], v[172:175], v[196:199], v[122:125]
	v_mfma_f32_16x16x32_bf16 v[118:121], v[164:167], v[204:207], v[118:121]
	v_mfma_f32_16x16x32_bf16 v[114:117], v[172:175], v[204:207], v[114:117]
	v_mfma_f32_16x16x32_bf16 v[94:97], v[164:167], v[212:215], v[94:97]
	v_mfma_f32_16x16x32_bf16 v[86:89], v[172:175], v[212:215], v[86:89]
	v_mfma_f32_16x16x32_bf16 v[54:57], v[164:167], v[220:223], v[54:57]
	v_mfma_f32_16x16x32_bf16 v[50:53], v[172:175], v[220:223], v[50:53]
	s_setprio 0
	s_setprio 1
	v_mfma_f32_16x16x32_bf16 v[110:113], v[176:179], v[192:195], v[110:113]
	v_mfma_f32_16x16x32_bf16 v[102:105], v[184:187], v[192:195], v[102:105]
	v_mfma_f32_16x16x32_bf16 v[78:81], v[176:179], v[200:203], v[78:81]
	v_mfma_f32_16x16x32_bf16 v[74:77], v[184:187], v[200:203], v[74:77]
	v_mfma_f32_16x16x32_bf16 v[30:33], v[176:179], v[208:211], v[30:33]
	v_mfma_f32_16x16x32_bf16 v[26:29], v[184:187], v[208:211], v[26:29]
	v_mfma_f32_16x16x32_bf16 v[10:13], v[176:179], v[216:219], v[10:13]
	v_mfma_f32_16x16x32_bf16 v[2:5], v[184:187], v[216:219], v[2:5]
	v_mfma_f32_16x16x32_bf16 v[110:113], v[180:183], v[196:199], v[110:113]
	v_mfma_f32_16x16x32_bf16 v[102:105], v[188:191], v[196:199], v[102:105]
	v_mfma_f32_16x16x32_bf16 v[78:81], v[180:183], v[204:207], v[78:81]
	v_mfma_f32_16x16x32_bf16 v[74:77], v[188:191], v[204:207], v[74:77]
	v_mfma_f32_16x16x32_bf16 v[30:33], v[180:183], v[212:215], v[30:33]
	v_mfma_f32_16x16x32_bf16 v[26:29], v[188:191], v[212:215], v[26:29]
	v_mfma_f32_16x16x32_bf16 v[10:13], v[180:183], v[220:223], v[10:13]
	v_mfma_f32_16x16x32_bf16 v[2:5], v[188:191], v[220:223], v[2:5]
	s_setprio 0
	s_barrier
	s_add_u32 s56, s56, 0x100
	s_addc_u32 s57, s57, 0
	s_add_u32 s83, s83, 0x100
	s_addc_u32 s84, s84, 0
	s_cmp_ge_i32 s25, s78
	s_mov_b32 s24, s25
	s_cbranch_scc0 .LBB0_587
	s_and_b64 vcc, exec, s[14:15]
	s_cbranch_vccz .LBB0_592
	s_barrier
	s_mov_b64 s[56:57], -1
	s_cmp_lg_u32 s5, 1
	v_lshl_or_b32 v150, s71, 8, v139
	s_cbranch_scc1 .LBB0_593

.LBB0_995:
	ds_read_b128 v[148:151], v160
	ds_read_b128 v[152:155], v160 offset:1024
	ds_read_b128 v[164:167], v160 offset:2048
	ds_read_b128 v[168:171], v160 offset:3072
	ds_read_b128 v[172:175], v161
	ds_read_b128 v[176:179], v161 offset:1024
	ds_read_b128 v[180:183], v161 offset:2048
	ds_read_b128 v[184:187], v161 offset:3072
	s_add_i32 s25, s24, 2
	s_add_u32 s23, s48, 0xfff80080
	s_addc_u32 s35, s49, -1
	s_cmp_eq_u32 s75, s24
	s_cselect_b32 s53, s15, s35
	s_cselect_b32 s52, s31, s23
	s_cselect_b32 s51, s73, s77
	s_cselect_b32 s50, s74, s76
	s_cselect_b64 s[100:101], s[38:39], -1
	v_lshl_add_u64 v[156:157], s[48:49], 0, v[140:141]
	s_add_i32 m0, s55, 0xc000
	ds_read_b128 v[188:191], v163
	ds_read_b128 v[192:195], v163 offset:1024
	ds_read_b128 v[196:199], v163 offset:2048
	ds_read_b128 v[200:203], v163 offset:3072
	ds_read_b128 v[204:207], v163 offset:4096
	ds_read_b128 v[208:211], v163 offset:5120
	ds_read_b128 v[212:215], v163 offset:6144
	ds_read_b128 v[216:219], v163 offset:7168
	global_load_lds_dwordx4 v[156:157], off
	v_lshl_add_u64 v[156:157], s[48:49], 0, v[142:143]
	s_add_i32 m0, s55, 0xe000
	s_nop 0
	global_load_lds_dwordx4 v[156:157], off
	s_waitcnt vmcnt(8)
	s_waitcnt lgkmcnt(0)
	s_barrier
	s_setprio 1
	s_waitcnt lgkmcnt(0)
	v_mfma_f32_16x16x32_bf16 v[78:81], v[148:151], v[188:191], v[78:81]
	v_mfma_f32_16x16x32_bf16 v[74:77], v[164:167], v[188:191], v[74:77]
	v_mfma_f32_16x16x32_bf16 v[70:73], v[148:151], v[196:199], v[70:73]
	v_mfma_f32_16x16x32_bf16 v[62:65], v[164:167], v[196:199], v[62:65]
	v_mfma_f32_16x16x32_bf16 v[54:57], v[148:151], v[204:207], v[54:57]
	v_mfma_f32_16x16x32_bf16 v[46:49], v[164:167], v[204:207], v[46:49]
	v_mfma_f32_16x16x32_bf16 v[38:41], v[148:151], v[212:215], v[38:41]
	v_mfma_f32_16x16x32_bf16 v[30:33], v[164:167], v[212:215], v[30:33]
	v_mfma_f32_16x16x32_bf16 v[78:81], v[152:155], v[192:195], v[78:81]
	v_mfma_f32_16x16x32_bf16 v[74:77], v[168:171], v[192:195], v[74:77]
	v_mfma_f32_16x16x32_bf16 v[70:73], v[152:155], v[200:203], v[70:73]
	v_mfma_f32_16x16x32_bf16 v[62:65], v[168:171], v[200:203], v[62:65]
	v_mfma_f32_16x16x32_bf16 v[54:57], v[152:155], v[208:211], v[54:57]
	v_mfma_f32_16x16x32_bf16 v[46:49], v[168:171], v[208:211], v[46:49]
	v_mfma_f32_16x16x32_bf16 v[38:41], v[152:155], v[216:219], v[38:41]
	v_mfma_f32_16x16x32_bf16 v[30:33], v[168:171], v[216:219], v[30:33]
	s_setprio 0
	s_setprio 1
	v_mfma_f32_16x16x32_bf16 v[50:53], v[172:175], v[188:191], v[50:53]
	v_mfma_f32_16x16x32_bf16 v[42:45], v[180:183], v[188:191], v[42:45]
	v_mfma_f32_16x16x32_bf16 v[34:37], v[172:175], v[196:199], v[34:37]
	v_mfma_f32_16x16x32_bf16 v[26:29], v[180:183], v[196:199], v[26:29]
	v_mfma_f32_16x16x32_bf16 v[22:25], v[172:175], v[204:207], v[22:25]
	v_mfma_f32_16x16x32_bf16 v[18:21], v[180:183], v[204:207], v[18:21]
	v_mfma_f32_16x16x32_bf16 v[10:13], v[172:175], v[212:215], v[10:13]
	v_mfma_f32_16x16x32_bf16 v[6:9], v[180:183], v[212:215], v[6:9]
	v_mfma_f32_16x16x32_bf16 v[50:53], v[176:179], v[192:195], v[50:53]
	v_mfma_f32_16x16x32_bf16 v[42:45], v[184:187], v[192:195], v[42:45]
	v_mfma_f32_16x16x32_bf16 v[34:37], v[176:179], v[200:203], v[34:37]
	v_mfma_f32_16x16x32_bf16 v[26:29], v[184:187], v[200:203], v[26:29]
	v_mfma_f32_16x16x32_bf16 v[22:25], v[176:179], v[208:211], v[22:25]
	v_mfma_f32_16x16x32_bf16 v[18:21], v[184:187], v[208:211], v[18:21]
	v_mfma_f32_16x16x32_bf16 v[10:13], v[176:179], v[216:219], v[10:13]
	v_mfma_f32_16x16x32_bf16 v[6:9], v[184:187], v[216:219], v[6:9]
	s_setprio 0
	s_barrier
	s_add_i32 s23, s68, s54
	v_lshl_add_u64 v[156:157], s[50:51], 0, v[132:133]
	s_mov_b32 m0, s23
	ds_read_b128 v[188:191], v163 offset:16384
	ds_read_b128 v[192:195], v163 offset:17408
	ds_read_b128 v[196:199], v163 offset:18432
	ds_read_b128 v[200:203], v163 offset:19456
	ds_read_b128 v[204:207], v163 offset:20480
	ds_read_b128 v[208:211], v163 offset:21504
	ds_read_b128 v[212:215], v163 offset:22528
	ds_read_b128 v[216:219], v163 offset:23552
	global_load_lds_dwordx4 v[156:157], off
	s_add_i32 m0, s23, 0x2000
	s_add_u32 s78, s50, 0x80000
	v_lshl_add_u64 v[220:221], s[50:51], 0, v[136:137]
	s_addc_u32 s79, s51, 0
	s_add_i32 s23, s69, s54
	global_load_lds_dwordx4 v[220:221], off
	v_lshl_add_u64 v[222:223], s[78:79], 0, v[132:133]
	s_mov_b32 m0, s23
	v_lshl_add_u64 v[224:225], s[52:53], 0, v[134:135]
	global_load_lds_dwordx4 v[222:223], off
	v_lshl_add_u64 v[222:223], s[78:79], 0, v[136:137]
	s_add_i32 m0, s23, 0x2000
	s_nop 0
	global_load_lds_dwordx4 v[222:223], off
	v_lshl_add_u64 v[222:223], s[52:53], 0, v[130:131]
	s_mov_b32 m0, s55
	s_nop 0
	global_load_lds_dwordx4 v[222:223], off
	s_mov_b32 m0, s56
	s_nop 0
	global_load_lds_dwordx4 v[224:225], off
	s_waitcnt vmcnt(8)
	s_waitcnt lgkmcnt(0)
	s_barrier
	s_setprio 1
	s_waitcnt lgkmcnt(0)
	v_mfma_f32_16x16x32_bf16 v[126:129], v[148:151], v[188:191], v[126:129]
	v_mfma_f32_16x16x32_bf16 v[122:125], v[164:167], v[188:191], v[122:125]
	v_mfma_f32_16x16x32_bf16 v[110:113], v[148:151], v[196:199], v[110:113]
	v_mfma_f32_16x16x32_bf16 v[106:109], v[164:167], v[196:199], v[106:109]
	v_mfma_f32_16x16x32_bf16 v[94:97], v[148:151], v[204:207], v[94:97]
	v_mfma_f32_16x16x32_bf16 v[90:93], v[164:167], v[204:207], v[90:93]
	v_mfma_f32_16x16x32_bf16 v[66:69], v[148:151], v[212:215], v[66:69]
	v_mfma_f32_16x16x32_bf16 v[58:61], v[164:167], v[212:215], v[58:61]
	v_mfma_f32_16x16x32_bf16 v[126:129], v[152:155], v[192:195], v[126:129]
	v_mfma_f32_16x16x32_bf16 v[122:125], v[168:171], v[192:195], v[122:125]
	v_mfma_f32_16x16x32_bf16 v[110:113], v[152:155], v[200:203], v[110:113]
	v_mfma_f32_16x16x32_bf16 v[106:109], v[168:171], v[200:203], v[106:109]
	v_mfma_f32_16x16x32_bf16 v[94:97], v[152:155], v[208:211], v[94:97]
	v_mfma_f32_16x16x32_bf16 v[90:93], v[168:171], v[208:211], v[90:93]
	v_mfma_f32_16x16x32_bf16 v[66:69], v[152:155], v[216:219], v[66:69]
	v_mfma_f32_16x16x32_bf16 v[58:61], v[168:171], v[216:219], v[58:61]
	s_setprio 0
	s_setprio 1
	v_mfma_f32_16x16x32_bf16 v[118:121], v[172:175], v[188:191], v[118:121]
	v_mfma_f32_16x16x32_bf16 v[114:117], v[180:183], v[188:191], v[114:117]
	v_mfma_f32_16x16x32_bf16 v[102:105], v[172:175], v[196:199], v[102:105]
	v_mfma_f32_16x16x32_bf16 v[98:101], v[180:183], v[196:199], v[98:101]
	v_mfma_f32_16x16x32_bf16 v[86:89], v[172:175], v[204:207], v[86:89]
	v_mfma_f32_16x16x32_bf16 v[82:85], v[180:183], v[204:207], v[82:85]
	v_mfma_f32_16x16x32_bf16 v[14:17], v[172:175], v[212:215], v[14:17]
	v_mfma_f32_16x16x32_bf16 v[2:5], v[180:183], v[212:215], v[2:5]
	v_mfma_f32_16x16x32_bf16 v[118:121], v[176:179], v[192:195], v[118:121]
	v_mfma_f32_16x16x32_bf16 v[114:117], v[184:187], v[192:195], v[114:117]
	v_mfma_f32_16x16x32_bf16 v[102:105], v[176:179], v[200:203], v[102:105]
	v_mfma_f32_16x16x32_bf16 v[98:101], v[184:187], v[200:203], v[98:101]
	v_mfma_f32_16x16x32_bf16 v[86:89], v[176:179], v[208:211], v[86:89]
	v_mfma_f32_16x16x32_bf16 v[82:85], v[184:187], v[208:211], v[82:85]
	v_mfma_f32_16x16x32_bf16 v[14:17], v[176:179], v[216:219], v[14:17]
	v_mfma_f32_16x16x32_bf16 v[2:5], v[184:187], v[216:219], v[2:5]
	s_setprio 0
	s_barrier
	s_add_i32 s23, 0, 0x18000
	s_add_i32 s24, 0, 0x1c000
	v_add_u32_e32 v168, s23, v158
	v_add_u32_e32 v184, s24, v158
	ds_read_b128 v[148:151], v168
	ds_read_b128 v[152:155], v168 offset:1024
	ds_read_b128 v[164:167], v168 offset:2048
	ds_read_b128 v[168:171], v168 offset:3072
	ds_read_b128 v[172:175], v184
	ds_read_b128 v[176:179], v184 offset:1024
	ds_read_b128 v[180:183], v184 offset:2048
	ds_read_b128 v[184:187], v184 offset:3072
	s_add_u32 s52, s52, 0x80000
	s_addc_u32 s53, s53, 0
	s_mov_b32 m0, s57
	v_lshl_add_u64 v[226:227], s[52:53], 0, v[130:131]
	ds_read_b128 v[188:191], v163 offset:32768
	ds_read_b128 v[192:195], v163 offset:33792
	ds_read_b128 v[196:199], v163 offset:34816
	ds_read_b128 v[200:203], v163 offset:35840
	ds_read_b128 v[204:207], v163 offset:36864
	ds_read_b128 v[208:211], v163 offset:37888
	ds_read_b128 v[212:215], v163 offset:38912
	ds_read_b128 v[216:219], v163 offset:39936
	s_mov_b64 exec, s[100:101]
	global_load_lds_dwordx4 v[226:227], off
	s_mov_b64 exec, -1
	v_lshl_add_u64 v[226:227], s[52:53], 0, v[134:135]
	s_mov_b32 m0, s58
	s_nop 0
	s_mov_b64 exec, s[100:101]
	global_load_lds_dwordx4 v[226:227], off
	s_mov_b64 exec, -1
	s_waitcnt vmcnt(8)
	s_waitcnt lgkmcnt(0)
	s_barrier
	s_setprio 1
	s_waitcnt lgkmcnt(0)
	v_mfma_f32_16x16x32_bf16 v[78:81], v[148:151], v[188:191], v[78:81]
	v_mfma_f32_16x16x32_bf16 v[74:77], v[164:167], v[188:191], v[74:77]
	v_mfma_f32_16x16x32_bf16 v[70:73], v[148:151], v[196:199], v[70:73]
	v_mfma_f32_16x16x32_bf16 v[62:65], v[164:167], v[196:199], v[62:65]
	v_mfma_f32_16x16x32_bf16 v[54:57], v[148:151], v[204:207], v[54:57]
	v_mfma_f32_16x16x32_bf16 v[46:49], v[164:167], v[204:207], v[46:49]
	v_mfma_f32_16x16x32_bf16 v[38:41], v[148:151], v[212:215], v[38:41]
	v_mfma_f32_16x16x32_bf16 v[30:33], v[164:167], v[212:215], v[30:33]
	v_mfma_f32_16x16x32_bf16 v[78:81], v[152:155], v[192:195], v[78:81]
	v_mfma_f32_16x16x32_bf16 v[74:77], v[168:171], v[192:195], v[74:77]
	v_mfma_f32_16x16x32_bf16 v[70:73], v[152:155], v[200:203], v[70:73]
	v_mfma_f32_16x16x32_bf16 v[62:65], v[168:171], v[200:203], v[62:65]
	v_mfma_f32_16x16x32_bf16 v[54:57], v[152:155], v[208:211], v[54:57]
	v_mfma_f32_16x16x32_bf16 v[46:49], v[168:171], v[208:211], v[46:49]
	v_mfma_f32_16x16x32_bf16 v[38:41], v[152:155], v[216:219], v[38:41]
	v_mfma_f32_16x16x32_bf16 v[30:33], v[168:171], v[216:219], v[30:33]
	s_setprio 0
	s_setprio 1
	v_mfma_f32_16x16x32_bf16 v[50:53], v[172:175], v[188:191], v[50:53]
	v_mfma_f32_16x16x32_bf16 v[42:45], v[180:183], v[188:191], v[42:45]
	v_mfma_f32_16x16x32_bf16 v[34:37], v[172:175], v[196:199], v[34:37]
	v_mfma_f32_16x16x32_bf16 v[26:29], v[180:183], v[196:199], v[26:29]
	v_mfma_f32_16x16x32_bf16 v[22:25], v[172:175], v[204:207], v[22:25]
	v_mfma_f32_16x16x32_bf16 v[18:21], v[180:183], v[204:207], v[18:21]
	v_mfma_f32_16x16x32_bf16 v[10:13], v[172:175], v[212:215], v[10:13]
	v_mfma_f32_16x16x32_bf16 v[6:9], v[180:183], v[212:215], v[6:9]
	v_mfma_f32_16x16x32_bf16 v[50:53], v[176:179], v[192:195], v[50:53]
	v_mfma_f32_16x16x32_bf16 v[42:45], v[184:187], v[192:195], v[42:45]
	v_mfma_f32_16x16x32_bf16 v[34:37], v[176:179], v[200:203], v[34:37]
	v_mfma_f32_16x16x32_bf16 v[26:29], v[184:187], v[200:203], v[26:29]
	v_mfma_f32_16x16x32_bf16 v[22:25], v[176:179], v[208:211], v[22:25]
	v_mfma_f32_16x16x32_bf16 v[18:21], v[184:187], v[208:211], v[18:21]
	v_mfma_f32_16x16x32_bf16 v[10:13], v[176:179], v[216:219], v[10:13]
	v_mfma_f32_16x16x32_bf16 v[6:9], v[184:187], v[216:219], v[6:9]
	s_setprio 0
	s_barrier
	s_add_i32 s23, s23, s54
	v_lshl_add_u64 v[156:157], v[156:157], 0, s[8:9]
	s_mov_b32 m0, s23
	ds_read_b128 v[188:191], v163 offset:49152
	ds_read_b128 v[192:195], v163 offset:50176
	ds_read_b128 v[196:199], v163 offset:51200
	ds_read_b128 v[200:203], v163 offset:52224
	ds_read_b128 v[204:207], v163 offset:53248
	ds_read_b128 v[208:211], v163 offset:54272
	ds_read_b128 v[212:215], v163 offset:55296
	ds_read_b128 v[216:219], v163 offset:56320
	s_mov_b64 exec, s[100:101]
	global_load_lds_dwordx4 v[156:157], off
	s_mov_b64 exec, -1
	s_add_i32 m0, s23, 0x2000
	s_add_u32 s50, s50, 0x80080
	v_lshl_add_u64 v[156:157], v[220:221], 0, s[8:9]
	s_addc_u32 s51, s51, 0
	s_add_i32 s23, s24, s54
	s_mov_b64 exec, s[100:101]
	global_load_lds_dwordx4 v[156:157], off
	s_mov_b64 exec, -1
	v_lshl_add_u64 v[156:157], s[50:51], 0, v[132:133]
	s_mov_b32 m0, s23
	s_nop 0
	s_mov_b64 exec, s[100:101]
	global_load_lds_dwordx4 v[156:157], off
	s_mov_b64 exec, -1
	v_lshl_add_u64 v[156:157], s[50:51], 0, v[136:137]
	s_add_i32 m0, s23, 0x2000
	s_nop 0
	s_mov_b64 exec, s[100:101]
	global_load_lds_dwordx4 v[156:157], off
	s_mov_b64 exec, -1
	v_lshl_add_u64 v[156:157], v[222:223], 0, s[8:9]
	s_mov_b32 m0, s63
	s_nop 0
	s_mov_b64 exec, s[100:101]
	global_load_lds_dwordx4 v[156:157], off
	s_mov_b64 exec, -1
	v_lshl_add_u64 v[156:157], v[224:225], 0, s[8:9]
	s_mov_b32 m0, s64
	s_nop 0
	s_mov_b64 exec, s[100:101]
	global_load_lds_dwordx4 v[156:157], off
	s_mov_b64 exec, -1
	s_waitcnt vmcnt(8)
	s_waitcnt lgkmcnt(0)
	s_barrier
	s_setprio 1
	s_waitcnt lgkmcnt(0)
	v_mfma_f32_16x16x32_bf16 v[126:129], v[148:151], v[188:191], v[126:129]
	v_mfma_f32_16x16x32_bf16 v[122:125], v[164:167], v[188:191], v[122:125]
	v_mfma_f32_16x16x32_bf16 v[110:113], v[148:151], v[196:199], v[110:113]
	v_mfma_f32_16x16x32_bf16 v[106:109], v[164:167], v[196:199], v[106:109]
	v_mfma_f32_16x16x32_bf16 v[94:97], v[148:151], v[204:207], v[94:97]
	v_mfma_f32_16x16x32_bf16 v[90:93], v[164:167], v[204:207], v[90:93]
	v_mfma_f32_16x16x32_bf16 v[66:69], v[148:151], v[212:215], v[66:69]
	v_mfma_f32_16x16x32_bf16 v[58:61], v[164:167], v[212:215], v[58:61]
	v_mfma_f32_16x16x32_bf16 v[126:129], v[152:155], v[192:195], v[126:129]
	v_mfma_f32_16x16x32_bf16 v[122:125], v[168:171], v[192:195], v[122:125]
	v_mfma_f32_16x16x32_bf16 v[110:113], v[152:155], v[200:203], v[110:113]
	v_mfma_f32_16x16x32_bf16 v[106:109], v[168:171], v[200:203], v[106:109]
	v_mfma_f32_16x16x32_bf16 v[94:97], v[152:155], v[208:211], v[94:97]
	v_mfma_f32_16x16x32_bf16 v[90:93], v[168:171], v[208:211], v[90:93]
	v_mfma_f32_16x16x32_bf16 v[66:69], v[152:155], v[216:219], v[66:69]
	v_mfma_f32_16x16x32_bf16 v[58:61], v[168:171], v[216:219], v[58:61]
	s_setprio 0
	s_setprio 1
	v_mfma_f32_16x16x32_bf16 v[118:121], v[172:175], v[188:191], v[118:121]
	v_mfma_f32_16x16x32_bf16 v[114:117], v[180:183], v[188:191], v[114:117]
	v_mfma_f32_16x16x32_bf16 v[102:105], v[172:175], v[196:199], v[102:105]
	v_mfma_f32_16x16x32_bf16 v[98:101], v[180:183], v[196:199], v[98:101]
	v_mfma_f32_16x16x32_bf16 v[86:89], v[172:175], v[204:207], v[86:89]
	v_mfma_f32_16x16x32_bf16 v[82:85], v[180:183], v[204:207], v[82:85]
	v_mfma_f32_16x16x32_bf16 v[14:17], v[172:175], v[212:215], v[14:17]
	v_mfma_f32_16x16x32_bf16 v[2:5], v[180:183], v[212:215], v[2:5]
	v_mfma_f32_16x16x32_bf16 v[118:121], v[176:179], v[192:195], v[118:121]
	v_mfma_f32_16x16x32_bf16 v[114:117], v[184:187], v[192:195], v[114:117]
	v_mfma_f32_16x16x32_bf16 v[102:105], v[176:179], v[200:203], v[102:105]
	v_mfma_f32_16x16x32_bf16 v[98:101], v[184:187], v[200:203], v[98:101]
	v_mfma_f32_16x16x32_bf16 v[86:89], v[176:179], v[208:211], v[86:89]
	v_mfma_f32_16x16x32_bf16 v[82:85], v[184:187], v[208:211], v[82:85]
	v_mfma_f32_16x16x32_bf16 v[14:17], v[176:179], v[216:219], v[14:17]
	v_mfma_f32_16x16x32_bf16 v[2:5], v[184:187], v[216:219], v[2:5]
	s_setprio 0
	s_barrier
	s_add_u32 s48, s48, 0x100
	s_addc_u32 s49, s49, 0
	s_add_u32 s76, s76, 0x100
	s_addc_u32 s77, s77, 0
	s_cmp_ge_i32 s25, s72
	s_mov_b32 s24, s25
	s_cbranch_scc0 .LBB0_995
	s_and_b64 vcc, exec, s[10:11]
	s_cbranch_vccz .LBB0_998
	s_barrier

.LBB0_1248:
	ds_read_b128 v[146:149], v159
	ds_read_b128 v[150:153], v159 offset:1024
	ds_read_b128 v[164:167], v159 offset:2048
	ds_read_b128 v[168:171], v159 offset:3072
	ds_read_b128 v[172:175], v160
	ds_read_b128 v[176:179], v160 offset:1024
	ds_read_b128 v[180:183], v160 offset:2048
	ds_read_b128 v[184:187], v160 offset:3072
	s_add_i32 s25, s24, 2
	s_add_u32 s42, s38, 0xffea0080
	s_addc_u32 s43, s39, -1
	s_cmp_eq_u32 s70, s24
	s_cselect_b32 s45, s66, s43
	s_cselect_b32 s44, s67, s42
	s_cselect_b32 s43, s68, s72
	s_cselect_b32 s42, s69, s71
	s_cselect_b64 s[100:101], s[28:29], -1
	v_lshl_add_u64 v[154:155], s[38:39], 0, v[138:139]
	s_add_i32 m0, s33, 0xc000
	ds_read_b128 v[188:191], v161
	ds_read_b128 v[192:195], v161 offset:1024
	ds_read_b128 v[196:199], v161 offset:2048
	ds_read_b128 v[200:203], v161 offset:3072
	ds_read_b128 v[204:207], v161 offset:4096
	ds_read_b128 v[208:211], v161 offset:5120
	ds_read_b128 v[212:215], v161 offset:6144
	ds_read_b128 v[216:219], v161 offset:7168
	global_load_lds_dwordx4 v[154:155], off
	v_lshl_add_u64 v[154:155], s[38:39], 0, v[140:141]
	s_add_i32 m0, s33, 0xe000
	s_nop 0
	global_load_lds_dwordx4 v[154:155], off
	s_waitcnt vmcnt(8)
	s_waitcnt lgkmcnt(0)
	s_barrier
	s_setprio 1
	s_waitcnt lgkmcnt(0)
	v_mfma_f32_16x16x32_bf16 v[76:79], v[146:149], v[188:191], v[76:79]
	v_mfma_f32_16x16x32_bf16 v[72:75], v[164:167], v[188:191], v[72:75]
	v_mfma_f32_16x16x32_bf16 v[64:67], v[146:149], v[196:199], v[64:67]
	v_mfma_f32_16x16x32_bf16 v[56:59], v[164:167], v[196:199], v[56:59]
	v_mfma_f32_16x16x32_bf16 v[52:55], v[146:149], v[204:207], v[52:55]
	v_mfma_f32_16x16x32_bf16 v[44:47], v[164:167], v[204:207], v[44:47]
	v_mfma_f32_16x16x32_bf16 v[36:39], v[146:149], v[212:215], v[36:39]
	v_mfma_f32_16x16x32_bf16 v[28:31], v[164:167], v[212:215], v[28:31]
	v_mfma_f32_16x16x32_bf16 v[76:79], v[150:153], v[192:195], v[76:79]
	v_mfma_f32_16x16x32_bf16 v[72:75], v[168:171], v[192:195], v[72:75]
	v_mfma_f32_16x16x32_bf16 v[64:67], v[150:153], v[200:203], v[64:67]
	v_mfma_f32_16x16x32_bf16 v[56:59], v[168:171], v[200:203], v[56:59]
	v_mfma_f32_16x16x32_bf16 v[52:55], v[150:153], v[208:211], v[52:55]
	v_mfma_f32_16x16x32_bf16 v[44:47], v[168:171], v[208:211], v[44:47]
	v_mfma_f32_16x16x32_bf16 v[36:39], v[150:153], v[216:219], v[36:39]
	v_mfma_f32_16x16x32_bf16 v[28:31], v[168:171], v[216:219], v[28:31]
	s_setprio 0
	s_setprio 1
	v_mfma_f32_16x16x32_bf16 v[48:51], v[172:175], v[188:191], v[48:51]
	v_mfma_f32_16x16x32_bf16 v[40:43], v[180:183], v[188:191], v[40:43]
	v_mfma_f32_16x16x32_bf16 v[32:35], v[172:175], v[196:199], v[32:35]
	v_mfma_f32_16x16x32_bf16 v[24:27], v[180:183], v[196:199], v[24:27]
	v_mfma_f32_16x16x32_bf16 v[20:23], v[172:175], v[204:207], v[20:23]
	v_mfma_f32_16x16x32_bf16 v[16:19], v[180:183], v[204:207], v[16:19]
	v_mfma_f32_16x16x32_bf16 v[8:11], v[172:175], v[212:215], v[8:11]
	v_mfma_f32_16x16x32_bf16 v[4:7], v[180:183], v[212:215], v[4:7]
	v_mfma_f32_16x16x32_bf16 v[48:51], v[176:179], v[192:195], v[48:51]
	v_mfma_f32_16x16x32_bf16 v[40:43], v[184:187], v[192:195], v[40:43]
	v_mfma_f32_16x16x32_bf16 v[32:35], v[176:179], v[200:203], v[32:35]
	v_mfma_f32_16x16x32_bf16 v[24:27], v[184:187], v[200:203], v[24:27]
	v_mfma_f32_16x16x32_bf16 v[20:23], v[176:179], v[208:211], v[20:23]
	v_mfma_f32_16x16x32_bf16 v[16:19], v[184:187], v[208:211], v[16:19]
	v_mfma_f32_16x16x32_bf16 v[8:11], v[176:179], v[216:219], v[8:11]
	v_mfma_f32_16x16x32_bf16 v[4:7], v[184:187], v[216:219], v[4:7]
	s_setprio 0
	s_barrier
	s_add_i32 s24, s58, s23
	v_lshl_add_u64 v[154:155], s[42:43], 0, v[130:131]
	s_mov_b32 m0, s24
	ds_read_b128 v[188:191], v161 offset:16384
	ds_read_b128 v[192:195], v161 offset:17408
	ds_read_b128 v[196:199], v161 offset:18432
	ds_read_b128 v[200:203], v161 offset:19456
	ds_read_b128 v[204:207], v161 offset:20480
	ds_read_b128 v[208:211], v161 offset:21504
	ds_read_b128 v[212:215], v161 offset:22528
	ds_read_b128 v[216:219], v161 offset:23552
	global_load_lds_dwordx4 v[154:155], off
	s_add_i32 m0, s24, 0x2000
	s_add_u32 s74, s42, 0x160000
	v_lshl_add_u64 v[220:221], s[42:43], 0, v[134:135]
	s_addc_u32 s75, s43, 0
	s_add_i32 s24, s59, s23
	global_load_lds_dwordx4 v[220:221], off
	v_lshl_add_u64 v[222:223], s[74:75], 0, v[130:131]
	s_mov_b32 m0, s24
	v_lshl_add_u64 v[224:225], s[44:45], 0, v[132:133]
	global_load_lds_dwordx4 v[222:223], off
	v_lshl_add_u64 v[222:223], s[74:75], 0, v[134:135]
	s_add_i32 m0, s24, 0x2000
	s_nop 0
	global_load_lds_dwordx4 v[222:223], off
	v_lshl_add_u64 v[222:223], s[44:45], 0, v[128:129]
	s_mov_b32 m0, s33
	s_nop 0
	global_load_lds_dwordx4 v[222:223], off
	s_mov_b32 m0, s46
	s_nop 0
	global_load_lds_dwordx4 v[224:225], off
	s_waitcnt vmcnt(8)
	s_waitcnt lgkmcnt(0)
	s_barrier
	s_setprio 1
	s_waitcnt lgkmcnt(0)
	v_mfma_f32_16x16x32_bf16 v[124:127], v[146:149], v[188:191], v[124:127]
	v_mfma_f32_16x16x32_bf16 v[120:123], v[164:167], v[188:191], v[120:123]
	v_mfma_f32_16x16x32_bf16 v[108:111], v[146:149], v[196:199], v[108:111]
	v_mfma_f32_16x16x32_bf16 v[104:107], v[164:167], v[196:199], v[104:107]
	v_mfma_f32_16x16x32_bf16 v[92:95], v[146:149], v[204:207], v[92:95]
	v_mfma_f32_16x16x32_bf16 v[88:91], v[164:167], v[204:207], v[88:91]
	v_mfma_f32_16x16x32_bf16 v[68:71], v[146:149], v[212:215], v[68:71]
	v_mfma_f32_16x16x32_bf16 v[60:63], v[164:167], v[212:215], v[60:63]
	v_mfma_f32_16x16x32_bf16 v[124:127], v[150:153], v[192:195], v[124:127]
	v_mfma_f32_16x16x32_bf16 v[120:123], v[168:171], v[192:195], v[120:123]
	v_mfma_f32_16x16x32_bf16 v[108:111], v[150:153], v[200:203], v[108:111]
	v_mfma_f32_16x16x32_bf16 v[104:107], v[168:171], v[200:203], v[104:107]
	v_mfma_f32_16x16x32_bf16 v[92:95], v[150:153], v[208:211], v[92:95]
	v_mfma_f32_16x16x32_bf16 v[88:91], v[168:171], v[208:211], v[88:91]
	v_mfma_f32_16x16x32_bf16 v[68:71], v[150:153], v[216:219], v[68:71]
	v_mfma_f32_16x16x32_bf16 v[60:63], v[168:171], v[216:219], v[60:63]
	s_setprio 0
	s_setprio 1
	v_mfma_f32_16x16x32_bf16 v[116:119], v[172:175], v[188:191], v[116:119]
	v_mfma_f32_16x16x32_bf16 v[112:115], v[180:183], v[188:191], v[112:115]
	v_mfma_f32_16x16x32_bf16 v[100:103], v[172:175], v[196:199], v[100:103]
	v_mfma_f32_16x16x32_bf16 v[96:99], v[180:183], v[196:199], v[96:99]
	v_mfma_f32_16x16x32_bf16 v[84:87], v[172:175], v[204:207], v[84:87]
	v_mfma_f32_16x16x32_bf16 v[80:83], v[180:183], v[204:207], v[80:83]
	v_mfma_f32_16x16x32_bf16 v[12:15], v[172:175], v[212:215], v[12:15]
	v_mfma_f32_16x16x32_bf16 v[0:3], v[180:183], v[212:215], v[0:3]
	v_mfma_f32_16x16x32_bf16 v[116:119], v[176:179], v[192:195], v[116:119]
	v_mfma_f32_16x16x32_bf16 v[112:115], v[184:187], v[192:195], v[112:115]
	v_mfma_f32_16x16x32_bf16 v[100:103], v[176:179], v[200:203], v[100:103]
	v_mfma_f32_16x16x32_bf16 v[96:99], v[184:187], v[200:203], v[96:99]
	v_mfma_f32_16x16x32_bf16 v[84:87], v[176:179], v[208:211], v[84:87]
	v_mfma_f32_16x16x32_bf16 v[80:83], v[184:187], v[208:211], v[80:83]
	v_mfma_f32_16x16x32_bf16 v[12:15], v[176:179], v[216:219], v[12:15]
	v_mfma_f32_16x16x32_bf16 v[0:3], v[184:187], v[216:219], v[0:3]
	s_setprio 0
	s_barrier
	s_add_i32 s24, 0, 0x18000
	v_add_u32_e32 v163, s24, v157
	s_add_i32 s73, 0, 0x1c000
	ds_read_b128 v[146:149], v163
	ds_read_b128 v[150:153], v163 offset:1024
	ds_read_b128 v[164:167], v163 offset:2048
	ds_read_b128 v[168:171], v163 offset:3072
	v_add_u32_e32 v163, s73, v157
	ds_read_b128 v[172:175], v163
	ds_read_b128 v[176:179], v163 offset:1024
	ds_read_b128 v[180:183], v163 offset:2048
	ds_read_b128 v[184:187], v163 offset:3072
	s_add_u32 s44, s44, 0x160000
	s_addc_u32 s45, s45, 0
	s_mov_b32 m0, s47
	v_lshl_add_u64 v[226:227], s[44:45], 0, v[128:129]
	ds_read_b128 v[188:191], v161 offset:32768
	ds_read_b128 v[192:195], v161 offset:33792
	ds_read_b128 v[196:199], v161 offset:34816
	ds_read_b128 v[200:203], v161 offset:35840
	ds_read_b128 v[204:207], v161 offset:36864
	ds_read_b128 v[208:211], v161 offset:37888
	ds_read_b128 v[212:215], v161 offset:38912
	ds_read_b128 v[216:219], v161 offset:39936
	s_mov_b64 exec, s[100:101]
	global_load_lds_dwordx4 v[226:227], off
	s_mov_b64 exec, -1
	v_lshl_add_u64 v[226:227], s[44:45], 0, v[132:133]
	s_mov_b32 m0, s48
	s_nop 0
	s_mov_b64 exec, s[100:101]
	global_load_lds_dwordx4 v[226:227], off
	s_mov_b64 exec, -1
	s_waitcnt vmcnt(8)
	s_waitcnt lgkmcnt(0)
	s_barrier
	s_setprio 1
	s_waitcnt lgkmcnt(0)
	v_mfma_f32_16x16x32_bf16 v[76:79], v[146:149], v[188:191], v[76:79]
	v_mfma_f32_16x16x32_bf16 v[72:75], v[164:167], v[188:191], v[72:75]
	v_mfma_f32_16x16x32_bf16 v[64:67], v[146:149], v[196:199], v[64:67]
	v_mfma_f32_16x16x32_bf16 v[56:59], v[164:167], v[196:199], v[56:59]
	v_mfma_f32_16x16x32_bf16 v[52:55], v[146:149], v[204:207], v[52:55]
	v_mfma_f32_16x16x32_bf16 v[44:47], v[164:167], v[204:207], v[44:47]
	v_mfma_f32_16x16x32_bf16 v[36:39], v[146:149], v[212:215], v[36:39]
	v_mfma_f32_16x16x32_bf16 v[28:31], v[164:167], v[212:215], v[28:31]
	v_mfma_f32_16x16x32_bf16 v[76:79], v[150:153], v[192:195], v[76:79]
	v_mfma_f32_16x16x32_bf16 v[72:75], v[168:171], v[192:195], v[72:75]
	v_mfma_f32_16x16x32_bf16 v[64:67], v[150:153], v[200:203], v[64:67]
	v_mfma_f32_16x16x32_bf16 v[56:59], v[168:171], v[200:203], v[56:59]
	v_mfma_f32_16x16x32_bf16 v[52:55], v[150:153], v[208:211], v[52:55]
	v_mfma_f32_16x16x32_bf16 v[44:47], v[168:171], v[208:211], v[44:47]
	v_mfma_f32_16x16x32_bf16 v[36:39], v[150:153], v[216:219], v[36:39]
	v_mfma_f32_16x16x32_bf16 v[28:31], v[168:171], v[216:219], v[28:31]
	s_setprio 0
	s_setprio 1
	v_mfma_f32_16x16x32_bf16 v[48:51], v[172:175], v[188:191], v[48:51]
	v_mfma_f32_16x16x32_bf16 v[40:43], v[180:183], v[188:191], v[40:43]
	v_mfma_f32_16x16x32_bf16 v[32:35], v[172:175], v[196:199], v[32:35]
	v_mfma_f32_16x16x32_bf16 v[24:27], v[180:183], v[196:199], v[24:27]
	v_mfma_f32_16x16x32_bf16 v[20:23], v[172:175], v[204:207], v[20:23]
	v_mfma_f32_16x16x32_bf16 v[16:19], v[180:183], v[204:207], v[16:19]
	v_mfma_f32_16x16x32_bf16 v[8:11], v[172:175], v[212:215], v[8:11]
	v_mfma_f32_16x16x32_bf16 v[4:7], v[180:183], v[212:215], v[4:7]
	v_mfma_f32_16x16x32_bf16 v[48:51], v[176:179], v[192:195], v[48:51]
	v_mfma_f32_16x16x32_bf16 v[40:43], v[184:187], v[192:195], v[40:43]
	v_mfma_f32_16x16x32_bf16 v[32:35], v[176:179], v[200:203], v[32:35]
	v_mfma_f32_16x16x32_bf16 v[24:27], v[184:187], v[200:203], v[24:27]
	v_mfma_f32_16x16x32_bf16 v[20:23], v[176:179], v[208:211], v[20:23]
	v_mfma_f32_16x16x32_bf16 v[16:19], v[184:187], v[208:211], v[16:19]
	v_mfma_f32_16x16x32_bf16 v[8:11], v[176:179], v[216:219], v[8:11]
	v_mfma_f32_16x16x32_bf16 v[4:7], v[184:187], v[216:219], v[4:7]
	s_setprio 0
	s_barrier
	s_add_i32 s24, s24, s23
	v_lshl_add_u64 v[154:155], v[154:155], 0, s[8:9]
	s_mov_b32 m0, s24
	ds_read_b128 v[188:191], v161 offset:49152
	ds_read_b128 v[192:195], v161 offset:50176
	ds_read_b128 v[196:199], v161 offset:51200
	ds_read_b128 v[200:203], v161 offset:52224
	ds_read_b128 v[204:207], v161 offset:53248
	ds_read_b128 v[208:211], v161 offset:54272
	ds_read_b128 v[212:215], v161 offset:55296
	ds_read_b128 v[216:219], v161 offset:56320
	s_mov_b64 exec, s[100:101]
	global_load_lds_dwordx4 v[154:155], off
	s_mov_b64 exec, -1
	s_add_i32 m0, s24, 0x2000
	s_add_u32 s42, s42, 0x160080
	v_lshl_add_u64 v[154:155], v[220:221], 0, s[8:9]
	s_addc_u32 s43, s43, 0
	s_add_i32 s24, s73, s23
	s_mov_b64 exec, s[100:101]
	global_load_lds_dwordx4 v[154:155], off
	s_mov_b64 exec, -1
	v_lshl_add_u64 v[154:155], s[42:43], 0, v[130:131]
	s_mov_b32 m0, s24
	s_nop 0
	s_mov_b64 exec, s[100:101]
	global_load_lds_dwordx4 v[154:155], off
	s_mov_b64 exec, -1
	v_lshl_add_u64 v[154:155], s[42:43], 0, v[134:135]
	s_add_i32 m0, s24, 0x2000
	s_nop 0
	s_mov_b64 exec, s[100:101]
	global_load_lds_dwordx4 v[154:155], off
	s_mov_b64 exec, -1
	v_lshl_add_u64 v[154:155], v[222:223], 0, s[8:9]
	s_mov_b32 m0, s54
	s_nop 0
	s_mov_b64 exec, s[100:101]
	global_load_lds_dwordx4 v[154:155], off
	s_mov_b64 exec, -1
	v_lshl_add_u64 v[154:155], v[224:225], 0, s[8:9]
	s_mov_b32 m0, s55
	s_nop 0
	s_mov_b64 exec, s[100:101]
	global_load_lds_dwordx4 v[154:155], off
	s_mov_b64 exec, -1
	s_waitcnt vmcnt(8)
	s_waitcnt lgkmcnt(0)
	s_barrier
	s_setprio 1
	s_waitcnt lgkmcnt(0)
	v_mfma_f32_16x16x32_bf16 v[124:127], v[146:149], v[188:191], v[124:127]
	v_mfma_f32_16x16x32_bf16 v[120:123], v[164:167], v[188:191], v[120:123]
	v_mfma_f32_16x16x32_bf16 v[108:111], v[146:149], v[196:199], v[108:111]
	v_mfma_f32_16x16x32_bf16 v[104:107], v[164:167], v[196:199], v[104:107]
	v_mfma_f32_16x16x32_bf16 v[92:95], v[146:149], v[204:207], v[92:95]
	v_mfma_f32_16x16x32_bf16 v[88:91], v[164:167], v[204:207], v[88:91]
	v_mfma_f32_16x16x32_bf16 v[68:71], v[146:149], v[212:215], v[68:71]
	v_mfma_f32_16x16x32_bf16 v[60:63], v[164:167], v[212:215], v[60:63]
	v_mfma_f32_16x16x32_bf16 v[124:127], v[150:153], v[192:195], v[124:127]
	v_mfma_f32_16x16x32_bf16 v[120:123], v[168:171], v[192:195], v[120:123]
	v_mfma_f32_16x16x32_bf16 v[108:111], v[150:153], v[200:203], v[108:111]
	v_mfma_f32_16x16x32_bf16 v[104:107], v[168:171], v[200:203], v[104:107]
	v_mfma_f32_16x16x32_bf16 v[92:95], v[150:153], v[208:211], v[92:95]
	v_mfma_f32_16x16x32_bf16 v[88:91], v[168:171], v[208:211], v[88:91]
	v_mfma_f32_16x16x32_bf16 v[68:71], v[150:153], v[216:219], v[68:71]
	v_mfma_f32_16x16x32_bf16 v[60:63], v[168:171], v[216:219], v[60:63]
	s_setprio 0
	s_setprio 1
	v_mfma_f32_16x16x32_bf16 v[116:119], v[172:175], v[188:191], v[116:119]
	v_mfma_f32_16x16x32_bf16 v[112:115], v[180:183], v[188:191], v[112:115]
	v_mfma_f32_16x16x32_bf16 v[100:103], v[172:175], v[196:199], v[100:103]
	v_mfma_f32_16x16x32_bf16 v[96:99], v[180:183], v[196:199], v[96:99]
	v_mfma_f32_16x16x32_bf16 v[84:87], v[172:175], v[204:207], v[84:87]
	v_mfma_f32_16x16x32_bf16 v[80:83], v[180:183], v[204:207], v[80:83]
	v_mfma_f32_16x16x32_bf16 v[12:15], v[172:175], v[212:215], v[12:15]
	v_mfma_f32_16x16x32_bf16 v[0:3], v[180:183], v[212:215], v[0:3]
	v_mfma_f32_16x16x32_bf16 v[116:119], v[176:179], v[192:195], v[116:119]
	v_mfma_f32_16x16x32_bf16 v[112:115], v[184:187], v[192:195], v[112:115]
	v_mfma_f32_16x16x32_bf16 v[100:103], v[176:179], v[200:203], v[100:103]
	v_mfma_f32_16x16x32_bf16 v[96:99], v[184:187], v[200:203], v[96:99]
	v_mfma_f32_16x16x32_bf16 v[84:87], v[176:179], v[208:211], v[84:87]
	v_mfma_f32_16x16x32_bf16 v[80:83], v[184:187], v[208:211], v[80:83]
	v_mfma_f32_16x16x32_bf16 v[12:15], v[176:179], v[216:219], v[12:15]
	v_mfma_f32_16x16x32_bf16 v[0:3], v[184:187], v[216:219], v[0:3]
	s_setprio 0
	s_barrier
	s_add_u32 s38, s38, 0x100
	s_addc_u32 s39, s39, 0
	s_add_u32 s71, s71, 0x100
	s_addc_u32 s72, s72, 0
	s_cmp_ge_i32 s25, s65
	s_mov_b32 s24, s25
	s_cbranch_scc0 .LBB0_1248
	s_and_b64 vcc, exec, s[10:11]
	s_cbranch_vccz .LBB0_1251
	s_barrier
